# prologue: the 64 S5-build workgroups also convert input rows (last 8192 rows), the other 192 stop at row 57344
# baseline (speedup 1.0000x reference)
; template <int MODE>
; __device__ __forceinline__ void e_phase(const Frame& F, const float* xin, bf16* X, const bf16* y, const float* rowpart, const float* gpost, float* rss, float* out) {
;     ...
;     const int gw = (MODE == 0 ? F.vcu - DEPTH * NG : F.vcu) * NWAVES + F.wave, NGW = (MODE == 0 ? F.G - DEPTH * NG : F.G) * NWAVES, lane = lane_;
;     f32x4 gp[2][2];
; #pragma unroll
;     for (int j = 0; j < 2; ++j)
; #pragma unroll
;         for (int n = 0; n < 2; ++n) gp[j][n] = MODE ? *(const f32x4*)(gpost + 8 * lane + 512 * j + 4 * n) : (f32x4){0.f, 0.f, 0.f, 0.f};
;     for (int m0 = (gw < 0 ? M : gw * ER); m0 < M; m0 += NGW * ER) {
;         v4u xv[ER][2], yv[ER][2]; f32x4 xf[ER][2][2]; float rp[ER];
; #pragma unroll
;         for (int r = 0; r < ER; ++r) { const size_t off = (size_t)(m0 + r) * DM + 8 * lane;
.LBB0_79:
	v_readlane_b32 s8, v252, 2
	v_readlane_b32 s9, v252, 3
	v_readlane_b32 s10, v252, 4
	v_readlane_b32 s11, v252, 5
	v_readlane_b32 s12, v252, 6
	v_readlane_b32 s13, v252, 7
	v_readlane_b32 s14, v252, 8
	v_readlane_b32 s15, v252, 9
	v_readlane_b32 s16, v252, 10
	v_readlane_b32 s17, v252, 11
	v_readlane_b32 s18, v252, 12
	v_readlane_b32 s19, v252, 13
	v_readlane_b32 s20, v252, 14
	v_readlane_b32 s21, v252, 15
	v_readlane_b32 s22, v252, 16
	v_readlane_b32 s23, v252, 17
	s_cmp_lt_u32 s33, 64
	s_cselect_b32 s0, 0x3a00, 0
	s_add_i32 s43, s43, s0
	s_cmpk_gt_u32 s43, 0x3fff
	s_mov_b64 s[36:37], s[8:9]
	v_readlane_b32 s8, v252, 18
	v_readlane_b32 s9, v252, 19
	v_readlane_b32 s10, v252, 20
	v_readlane_b32 s11, v252, 21
	v_readlane_b32 s12, v252, 22
	v_readlane_b32 s13, v252, 23
	v_readlane_b32 s14, v252, 24
	v_readlane_b32 s15, v252, 25
	v_readlane_b32 s16, v252, 26
	v_readlane_b32 s17, v252, 27
	v_readlane_b32 s18, v252, 28
	v_readlane_b32 s19, v252, 29
	v_readlane_b32 s20, v252, 30
	v_readlane_b32 s21, v252, 31
	v_readlane_b32 s22, v252, 32
	v_readlane_b32 s23, v252, 33
	s_cbranch_scc1 .LBB0_90
	s_lshl_b32 s0, s3, 5
	s_add_i32 s10, s0, 0xfffff800
	s_cmp_lt_u32 s33, 64
	s_cselect_b32 s10, 0x800, s10
	s_lshl_b32 s0, s33, 5
	s_lshl_b32 s1, s42, 2
	s_add_i32 s0, s0, s1
	v_lshlrev_b32_e32 v0, 3, v62
	s_addk_i32 s0, 0xf800
	s_lshl_b32 s0, s43, 2
	v_ashrrev_i32_e32 v1, 31, v0
	s_ashr_i32 s1, s0, 31
	s_ashr_i32 s11, s10, 31
	s_lshl_b64 s[16:17], s[0:1], 11
	v_lshlrev_b64 v[2:3], 1, v[0:1]
	s_lshl_b32 s8, s43, 2
	s_lshl_b64 s[12:13], s[0:1], 4
	s_lshl_b64 s[14:15], s[10:11], 4
	v_lshl_add_u64 v[52:53], s[16:17], 0, v[2:3]
	s_lshl_b64 s[16:17], s[10:11], 11
	s_lshl_b64 s[0:1], s[0:1], 12
	s_add_u32 s18, s36, s0
	s_addc_u32 s19, s37, s1
	s_ashr_i32 s9, s8, 31
	s_lshl_b64 s[20:21], s[10:11], 12
	s_lshl_b64 s[0:1], s[8:9], 4
	s_add_u32 s11, s0, 0x7400000
	v_lshlrev_b64 v[54:55], 2, v[0:1]
	s_addc_u32 s40, s1, 0
	s_lshl_b64 s[0:1], s[8:9], 11
	v_mbcnt_lo_u32_b32 v0, -1, 0
	v_lshl_add_u64 v[56:57], s[0:1], 0, v[2:3]
	s_lshl_b64 s[0:1], s[8:9], 12
	v_mbcnt_hi_u32_b32 v60, -1, v0
	s_add_u32 s22, s36, s0
	v_and_b32_e32 v0, 64, v60
	v_cmp_eq_u32_e32 vcc, 0, v62
	s_addc_u32 s23, s37, s1
	s_mov_b64 s[24:25], 0x1000
	s_movk_i32 s9, 0x1000
	s_mov_b64 s[26:27], 0x1800
	s_mov_b64 s[28:29], 0x2000
	s_movk_i32 s41, 0x2000
	s_mov_b64 s[30:31], 0x2800
	s_mov_b64 s[36:37], 0x3000
	s_movk_i32 s42, 0x3000
	s_mov_b64 s[38:39], 0x3800
	s_brev_b32 s43, 16
	v_add_u32_e32 v61, 64, v0
	v_xor_b32_e32 v62, 1, v60
	v_xor_b32_e32 v63, 2, v60
	v_xor_b32_e32 v64, 4, v60
	v_xor_b32_e32 v65, 8, v60
	v_xor_b32_e32 v66, 16, v60
	v_xor_b32_e32 v67, 32, v60
	v_mov_b32_e32 v1, 0
	v_mov_b32_e32 v68, 0x7400000
	s_mov_b32 s44, 0x8001000
	s_cmp_lt_u32 s33, 64
	s_cselect_b32 s0, 0, 0x2000
	s_add_i32 s8, s8, s0
	s_branch .LBB0_82
